# layer-0 input row phase: parameter set-up loop de-serialised (all 22 loads issued, one wait, then the LDS writes) on top of the session-best attention edits
# speedup vs baseline: 1.0097x; 1.0097x over previous
; template <bool HAS_Y, bool WRITE_X, bool HAS_XN> ...
;     for (int idx = tid; idx < 5 * DM; idx += NTHR) { const int r = idx >> 10, c = idx & (DM - 1);
;         if (HAS_Y) PRM[idx] = mods_y[((size_t)r * 6 + gate_idx) * DM + c] * ngy[c];
;         if (HAS_XN) { PRM[5 * DM + idx] = ng2[c] * (1.0f + mods_n[((size_t)r * 6 + sc_idx) * DM + c]); PRM[10 * DM + idx] = mods_n[((size_t)r * 6 + sh_idx) * DM + c]; } }
;     __syncthreads();
;     ...
;     RowRegs A, B, C, D;
;     int row = gw;
;     if (row < MROWS) {
;         row_load<HAS_Y>(A, row, ROW_ON(row), lane, xin_lat, xin_ctx, Y); row_load<HAS_Y>(B, row + NGW, ROW_ON(row + NGW), lane, xin_lat, xin_ctx, Y);
.LBB0_102:
	s_cmp_lt_i32 s84, 2
	s_cselect_b64 s[2:3], -1, 0
	s_waitcnt lgkmcnt(0)
	s_add_u32 s54, s90, 0x3c00000
	s_addc_u32 s55, s91, 0
	s_and_b64 s[0:1], s[2:3], s[0:1]
	s_andn2_b64 vcc, exec, s[0:1]
	s_cbranch_vccnz .LBB0_147
	v_lshl_add_u32 v2, v0, 2, 0
	v_add_u32_e32 v4, 0x5000, v2
	global_load_dword v8, v2, s[60:61]
	global_load_dword v9, v2, s[60:61] offset:2048
	s_add_u32 s2, s94, 0x0
	s_addc_u32 s3, s95, 0
	s_add_u32 s4, s2, 0x1000
	s_addc_u32 s5, s3, 0
	global_load_dword v10, v2, s[2:3]
	global_load_dword v11, v2, s[2:3] offset:2048
	global_load_dword v12, v2, s[4:5]
	global_load_dword v13, v2, s[4:5] offset:2048
	s_add_u32 s2, s94, 0x6000
	s_addc_u32 s3, s95, 0
	s_add_u32 s4, s2, 0x1000
	s_addc_u32 s5, s3, 0
	global_load_dword v14, v2, s[2:3]
	global_load_dword v15, v2, s[2:3] offset:2048
	global_load_dword v16, v2, s[4:5]
	global_load_dword v17, v2, s[4:5] offset:2048
	s_add_u32 s2, s94, 0xc000
	s_addc_u32 s3, s95, 0
	s_add_u32 s4, s2, 0x1000
	s_addc_u32 s5, s3, 0
	global_load_dword v18, v2, s[2:3]
	global_load_dword v19, v2, s[2:3] offset:2048
	global_load_dword v20, v2, s[4:5]
	global_load_dword v21, v2, s[4:5] offset:2048
	s_add_u32 s2, s94, 0x12000
	s_addc_u32 s3, s95, 0
	s_add_u32 s4, s2, 0x1000
	s_addc_u32 s5, s3, 0
	global_load_dword v22, v2, s[2:3]
	global_load_dword v23, v2, s[2:3] offset:2048
	global_load_dword v24, v2, s[4:5]
	global_load_dword v25, v2, s[4:5] offset:2048
	s_add_u32 s2, s94, 0x18000
	s_addc_u32 s3, s95, 0
	s_add_u32 s4, s2, 0x1000
	s_addc_u32 s5, s3, 0
	global_load_dword v26, v2, s[2:3]
	global_load_dword v27, v2, s[2:3] offset:2048
	global_load_dword v28, v2, s[4:5]
	global_load_dword v29, v2, s[4:5] offset:2048
	s_waitcnt vmcnt(0)
	v_add_f32_e32 v12, 1.0, v12
	v_mul_f32_e32 v12, v8, v12
	ds_write2st64_b32 v4, v12, v10 offset0:0 offset1:80
	v_add_f32_e32 v13, 1.0, v13
	v_mul_f32_e32 v13, v9, v13
	ds_write2st64_b32 v4, v13, v11 offset0:8 offset1:88
	v_add_f32_e32 v16, 1.0, v16
	v_mul_f32_e32 v16, v8, v16
	ds_write2st64_b32 v4, v16, v14 offset0:16 offset1:96
	v_add_f32_e32 v17, 1.0, v17
	v_mul_f32_e32 v17, v9, v17
	ds_write2st64_b32 v4, v17, v15 offset0:24 offset1:104
	v_add_f32_e32 v20, 1.0, v20
	v_mul_f32_e32 v20, v8, v20
	ds_write2st64_b32 v4, v20, v18 offset0:32 offset1:112
	v_add_f32_e32 v21, 1.0, v21
	v_mul_f32_e32 v21, v9, v21
	ds_write2st64_b32 v4, v21, v19 offset0:40 offset1:120
	v_add_f32_e32 v24, 1.0, v24
	v_mul_f32_e32 v24, v8, v24
	ds_write2st64_b32 v4, v24, v22 offset0:48 offset1:128
	v_add_f32_e32 v25, 1.0, v25
	v_mul_f32_e32 v25, v9, v25
	ds_write2st64_b32 v4, v25, v23 offset0:56 offset1:136
	v_add_f32_e32 v28, 1.0, v28
	v_mul_f32_e32 v28, v8, v28
	ds_write2st64_b32 v4, v28, v26 offset0:64 offset1:144
	v_add_f32_e32 v29, 1.0, v29
	v_mul_f32_e32 v29, v9, v29
	ds_write2st64_b32 v4, v29, v27 offset0:72 offset1:152
	s_cmp_lt_i32 s46, 0x8400
	s_waitcnt lgkmcnt(0)
	s_barrier
	s_cbranch_scc0 .LBB0_146
	s_mul_hi_i32 s2, s46, 0x3e0f83e1
	s_lshr_b32 s3, s2, 31
	s_ashr_i32 s5, s2, 11
	s_add_i32 s5, s5, s3
	s_mul_i32 s12, s5, 0xffffdf00
	s_add_i32 s12, s12, s46
	s_cmpk_lt_i32 s12, 0x2000
	s_cbranch_scc0 .LBB0_108
	s_lshl_b32 s2, s5, 13
	s_add_i32 s4, s12, s2
	s_mov_b64 s[2:3], s[48:49]
	s_cbranch_execz .LBB0_109
	s_branch .LBB0_110

; __global__ void __launch_bounds__(mk::NTHR, 2) fwd_kernel(Args args) {
;     ...
;     if (IN(13)) {
;         for (int u = vcu; u < 1024; u += G) { const int qb = u & 31, gq = (u >> 5) & 3, kvh = (u >> 7) & 1, b = u >> 8, h = kvh * 4 + gq;
.LBB0_1582:
	s_nop 0
	s_nop 0
	s_nop 0
	s_nop 0
	s_nop 0
	s_nop 0
	s_nop 0
	s_nop 0
	s_cmp_lt_i32 s84, 14
	s_cselect_b64 s[4:5], -1, 0
	s_and_b64 s[28:29], s[4:5], s[2:3]
	s_xor_b64 s[2:3], s[28:29], -1
	s_cmpk_gt_i32 s33, 0x3ff
	s_cselect_b64 s[4:5], -1, 0
	s_or_b64 s[2:3], s[2:3], s[4:5]
	s_and_b64 vcc, exec, s[2:3]
	s_cbranch_vccnz .LBB0_1602
	v_readfirstlane_b32 s98, v0
	s_bitcmp1_b32 s98, 8
	s_cbranch_scc0 .Lattn_noprio
	s_setprio 1
